# attention main loop: rescale decision any(rowmax > thr) taken on each lane's half-row max (same any()); the cross-half exchange (v_mov, permlane32_swap, v_max) and the flag materialisation moved into
# baseline (speedup 1.0000x reference)
.LBB0_1547:
	v_add_u32_e32 v0, s8, v221
	ds_read_b64_tr_b16 v[192:193], v0 offset:24576
	ds_read_b64_tr_b16 v[194:195], v0 offset:25088
	s_waitcnt lgkmcnt(9)
	v_mfma_f32_32x32x16_bf16 v[112:127], v[188:191], v[148:151], v[48:63]
	v_add_f32_e32 v2, v80, v81
	v_add_f32_e32 v2, v82, v2
	v_add_f32_e32 v2, v83, v2
	v_add_f32_e32 v2, v84, v2
	v_add_f32_e32 v2, v85, v2
	v_cvt_pk_bf16_f32 v156, v80, v81
	v_cvt_pk_bf16_f32 v157, v82, v83
	ds_read_b64_tr_b16 v[188:189], v0 offset:28672
	ds_read_b64_tr_b16 v[190:191], v0 offset:29184
	s_waitcnt lgkmcnt(10)
	v_mfma_f32_32x32x16_bf16 v[96:111], v[184:187], v[148:151], v[48:63]
	v_add_f32_e32 v2, v86, v2
	v_add_f32_e32 v2, v87, v2
	v_add_f32_e32 v2, v88, v2
	v_add_f32_e32 v2, v89, v2
	v_cvt_pk_bf16_f32 v158, v84, v85
	v_cvt_pk_bf16_f32 v159, v86, v87
	ds_read_b64_tr_b16 v[184:185], v0 offset:25600
	ds_read_b64_tr_b16 v[186:187], v0 offset:26112
	s_waitcnt lgkmcnt(11)
	v_mfma_f32_32x32x16_bf16 v[112:127], v[180:183], v[140:143], v[112:127]
	v_add_f32_e32 v2, v90, v2
	v_add_f32_e32 v2, v91, v2
	v_add_f32_e32 v2, v92, v2
	v_add_f32_e32 v2, v93, v2
	v_cvt_pk_bf16_f32 v152, v88, v89
	v_cvt_pk_bf16_f32 v153, v90, v91
	ds_read_b64_tr_b16 v[84:85], v0 offset:29696
	ds_read_b64_tr_b16 v[86:87], v0 offset:30208
	s_waitcnt lgkmcnt(12)
	v_mfma_f32_32x32x16_bf16 v[96:111], v[176:179], v[140:143], v[96:111]
	v_add_f32_e32 v2, v94, v2
	v_add_f32_e32 v2, v95, v2
	v_add_f32_e32 v2, v64, v2
	v_add_f32_e32 v2, v65, v2
	v_cvt_pk_bf16_f32 v154, v92, v93
	v_cvt_pk_bf16_f32 v155, v94, v95
	ds_read_b64_tr_b16 v[80:81], v0 offset:26624
	ds_read_b64_tr_b16 v[82:83], v0 offset:27136
	s_waitcnt lgkmcnt(13)
	v_mfma_f32_32x32x16_bf16 v[112:127], v[172:175], v[132:135], v[112:127]
	v_add_f32_e32 v2, v66, v2
	v_add_f32_e32 v2, v67, v2
	v_add_f32_e32 v2, v68, v2
	v_add_f32_e32 v2, v69, v2
	v_cvt_pk_bf16_f32 v144, v64, v65
	v_cvt_pk_bf16_f32 v145, v66, v67
	ds_read_b64_tr_b16 v[10:11], v0 offset:30720
	ds_read_b64_tr_b16 v[12:13], v0 offset:31232
	s_waitcnt lgkmcnt(14)
	v_mfma_f32_32x32x16_bf16 v[96:111], v[168:171], v[132:135], v[96:111]
	v_add_f32_e32 v2, v70, v2
	v_add_f32_e32 v2, v71, v2
	v_add_f32_e32 v2, v72, v2
	v_add_f32_e32 v2, v73, v2
	v_cvt_pk_bf16_f32 v146, v68, v69
	v_cvt_pk_bf16_f32 v147, v70, v71
	ds_read_b64_tr_b16 v[6:7], v0 offset:27648
	ds_read_b64_tr_b16 v[8:9], v0 offset:28160
	s_waitcnt lgkmcnt(14)
	v_mfma_f32_32x32x16_bf16 v[112:127], v[164:167], v[128:131], v[112:127]
	v_add_f32_e32 v2, v74, v2
	v_add_f32_e32 v2, v75, v2
	v_add_f32_e32 v2, v76, v2
	v_add_f32_e32 v14, v77, v2
	v_cvt_pk_bf16_f32 v136, v72, v73
	v_cvt_pk_bf16_f32 v137, v74, v75
	ds_read_b64_tr_b16 v[2:3], v0 offset:31744
	ds_read_b64_tr_b16 v[4:5], v0 offset:32256
	v_mfma_f32_32x32x16_bf16 v[96:111], v[160:163], v[128:131], v[96:111]
	v_add_f32_e32 v0, v78, v14
	v_add_f32_e32 v0, v79, v0
	v_cvt_pk_bf16_f32 v138, v76, v77
	v_cvt_pk_bf16_f32 v139, v78, v79
	v_lshl_add_u64 v[14:15], v[202:203], 0, s[26:27]
	s_add_i32 s8, s40, s46
	s_mov_b32 s9, m0
	s_mov_b32 m0, s8
	s_nop 0
	global_load_lds_dwordx4 v[14:15], off
	s_mov_b32 m0, s9
	v_lshl_add_u64 v[14:15], v[200:201], 0, s[26:27]
	s_add_i32 s8, s38, s47
	s_mov_b32 s9, m0
	s_mov_b32 m0, s8
	s_nop 0
	global_load_lds_dwordx4 v[14:15], off
	s_mov_b32 m0, s9
	v_max3_f32 v14, v112, v113, v114
	v_max3_f32 v15, v115, v116, v117
	v_max3_f32 v14, v14, v118, v119
	v_max3_f32 v15, v15, v120, v121
	v_max3_f32 v14, v14, v122, v123
	v_max3_f32 v15, v15, v124, v125
	v_max3_f32 v14, v14, v126, v127
	v_max3_f32 v15, v15, v96, v97
	v_max3_f32 v14, v14, v98, v99
	v_max3_f32 v15, v15, v100, v101
	v_max3_f32 v14, v14, v102, v103
	v_max3_f32 v15, v15, v104, v105
	v_max3_f32 v14, v14, v106, v107
	v_max3_f32 v15, v15, v108, v109
	v_max3_f32 v64, v14, v110, v111
	v_add_f32_e32 v14, v223, v0
	v_max_f32_e32 v0, v64, v15
	s_mov_b64 s[8:9], 0
	v_cmp_lt_f32_e32 vcc, s53, v0
	s_cbranch_vccnz .LBB0_1555

.LBB0_1550:
	s_add_i32 s8, s38, 0x2000
	s_cmpk_lg_i32 s38, 0x4000
	s_cselect_b32 s13, s8, 0
	v_add_u32_e32 v4, s40, v221
	ds_read_b64_tr_b16 v[168:169], v4 offset:24576
	ds_read_b64_tr_b16 v[170:171], v4 offset:25088
	s_waitcnt lgkmcnt(9)
	v_mfma_f32_32x32x16_bf16 v[80:95], v[64:67], v[148:151], v[48:63]
	v_add_f32_e32 v2, v112, v113
	v_add_f32_e32 v2, v114, v2
	v_add_f32_e32 v2, v115, v2
	v_add_f32_e32 v2, v116, v2
	v_add_f32_e32 v2, v117, v2
	v_cvt_pk_bf16_f32 v156, v112, v113
	v_cvt_pk_bf16_f32 v157, v114, v115
	ds_read_b64_tr_b16 v[164:165], v4 offset:28672
	ds_read_b64_tr_b16 v[166:167], v4 offset:29184
	s_waitcnt lgkmcnt(10)
	v_mfma_f32_32x32x16_bf16 v[64:79], v[160:163], v[148:151], v[48:63]
	v_add_f32_e32 v2, v118, v2
	v_add_f32_e32 v2, v119, v2
	v_add_f32_e32 v2, v120, v2
	v_add_f32_e32 v2, v121, v2
	v_cvt_pk_bf16_f32 v158, v116, v117
	v_cvt_pk_bf16_f32 v159, v118, v119
	ds_read_b64_tr_b16 v[160:161], v4 offset:25600
	ds_read_b64_tr_b16 v[162:163], v4 offset:26112
	s_waitcnt lgkmcnt(11)
	v_mfma_f32_32x32x16_bf16 v[80:95], v[192:195], v[140:143], v[80:95]
	v_add_f32_e32 v2, v122, v2
	v_add_f32_e32 v2, v123, v2
	v_add_f32_e32 v2, v124, v2
	v_add_f32_e32 v2, v125, v2
	v_cvt_pk_bf16_f32 v152, v120, v121
	v_cvt_pk_bf16_f32 v153, v122, v123
	ds_read_b64_tr_b16 v[116:117], v4 offset:29696
	ds_read_b64_tr_b16 v[118:119], v4 offset:30208
	s_waitcnt lgkmcnt(12)
	v_mfma_f32_32x32x16_bf16 v[64:79], v[184:187], v[140:143], v[64:79]
	v_add_f32_e32 v2, v126, v2
	v_add_f32_e32 v2, v127, v2
	v_add_f32_e32 v2, v96, v2
	v_add_f32_e32 v2, v97, v2
	v_cvt_pk_bf16_f32 v154, v124, v125
	v_cvt_pk_bf16_f32 v155, v126, v127
	ds_read_b64_tr_b16 v[112:113], v4 offset:26624
	ds_read_b64_tr_b16 v[114:115], v4 offset:27136
	s_waitcnt lgkmcnt(13)
	v_mfma_f32_32x32x16_bf16 v[80:95], v[188:191], v[132:135], v[80:95]
	v_add_f32_e32 v2, v98, v2
	v_add_f32_e32 v2, v99, v2
	v_add_f32_e32 v2, v100, v2
	v_add_f32_e32 v2, v101, v2
	v_cvt_pk_bf16_f32 v144, v96, v97
	v_cvt_pk_bf16_f32 v145, v98, v99
	ds_read_b64_tr_b16 v[10:11], v4 offset:30720
	ds_read_b64_tr_b16 v[12:13], v4 offset:31232
	s_waitcnt lgkmcnt(14)
	v_mfma_f32_32x32x16_bf16 v[64:79], v[176:179], v[132:135], v[64:79]
	v_add_f32_e32 v2, v102, v2
	v_add_f32_e32 v2, v103, v2
	v_add_f32_e32 v2, v104, v2
	v_add_f32_e32 v2, v105, v2
	v_cvt_pk_bf16_f32 v146, v100, v101
	v_cvt_pk_bf16_f32 v147, v102, v103
	ds_read_b64_tr_b16 v[6:7], v4 offset:27648
	ds_read_b64_tr_b16 v[8:9], v4 offset:28160
	s_waitcnt lgkmcnt(14)
	v_mfma_f32_32x32x16_bf16 v[80:95], v[180:183], v[128:131], v[80:95]
	v_add_f32_e32 v2, v106, v2
	v_add_f32_e32 v2, v107, v2
	v_add_f32_e32 v2, v108, v2
	v_add_f32_e32 v15, v109, v2
	v_cvt_pk_bf16_f32 v136, v104, v105
	v_cvt_pk_bf16_f32 v137, v106, v107
	ds_read_b64_tr_b16 v[2:3], v4 offset:31744
	ds_read_b64_tr_b16 v[4:5], v4 offset:32256
	v_mfma_f32_32x32x16_bf16 v[64:79], v[172:175], v[128:131], v[64:79]
	v_add_f32_e32 v15, v110, v15
	v_add_f32_e32 v15, v111, v15
	v_cvt_pk_bf16_f32 v138, v108, v109
	v_cvt_pk_bf16_f32 v139, v110, v111
	v_max3_f32 v96, v80, v81, v82
	v_max3_f32 v97, v83, v84, v85
	v_max3_f32 v96, v96, v86, v87
	v_max3_f32 v97, v97, v88, v89
	v_max3_f32 v96, v96, v90, v91
	v_max3_f32 v97, v97, v92, v93
	v_max3_f32 v96, v96, v94, v95
	v_add_f32_e32 v223, v14, v15
	s_nop 0
	v_max3_f32 v97, v97, v64, v65
	v_max3_f32 v96, v96, v66, v67
	v_max3_f32 v97, v97, v68, v69
	v_max3_f32 v96, v96, v70, v71
	v_max3_f32 v97, v97, v72, v73
	v_max3_f32 v96, v96, v74, v75
	v_max3_f32 v97, v97, v76, v77
	v_max3_f32 v96, v96, v78, v79
	v_max_f32_e32 v14, v96, v97
	s_add_i32 s8, s38, s46
	s_mov_b32 s9, m0
	s_mov_b32 m0, s8
	s_nop 0
	global_load_lds_dwordx4 v[202:203], off
	s_mov_b32 m0, s9
	s_add_i32 s8, s13, s47
	s_mov_b32 s9, m0
	s_mov_b32 m0, s8
	s_nop 0
	global_load_lds_dwordx4 v[200:201], off
	s_mov_b32 m0, s9
	s_mov_b64 s[8:9], 0
	v_cmp_lt_f32_e32 vcc, s53, v14
	s_cbranch_vccnz .LBB0_1558

.LBB0_1555:
	s_mov_b64 s[8:9], -1
	v_mov_b32_e32 v15, v0
	s_nop 1
	v_permlane32_swap_b32_e32 v0, v15
	v_max_f32_e32 v0, v0, v15
	v_max_f32_e32 v0, v0, v0
	v_max_f32_e32 v0, 0, v0
	v_exp_f32_e64 v15, -v0
	v_add_f32_e32 v219, v219, v0
	v_xor_b32_e32 v48, 0x80000000, v219
	v_mov_b32_e32 v49, v48
	v_mov_b32_e32 v50, v48
	v_mov_b32_e32 v51, v48
	v_mov_b32_e32 v52, v48
	v_mov_b32_e32 v53, v48
	v_mov_b32_e32 v54, v48
	v_mov_b32_e32 v55, v48
	v_mov_b32_e32 v56, v48
	v_mov_b32_e32 v57, v48
	v_mov_b32_e32 v58, v48
	v_mov_b32_e32 v59, v48
	v_mov_b32_e32 v60, v48
	v_mov_b32_e32 v61, v48
	v_mov_b32_e32 v62, v48
	v_mov_b32_e32 v63, v48
	s_and_saveexec_b64 s[34:35], s[6:7]
	ds_write_b32 v204, v15 offset:49152
	s_or_b64 exec, exec, s[34:35]
	v_sub_f32_e32 v127, v127, v0
	v_sub_f32_e32 v126, v126, v0
	v_sub_f32_e32 v125, v125, v0
	v_sub_f32_e32 v124, v124, v0
	v_sub_f32_e32 v123, v123, v0
	v_sub_f32_e32 v122, v122, v0
	v_sub_f32_e32 v121, v121, v0
	v_sub_f32_e32 v120, v120, v0
	v_sub_f32_e32 v119, v119, v0
	v_sub_f32_e32 v118, v118, v0
	v_sub_f32_e32 v117, v117, v0
	v_sub_f32_e32 v116, v116, v0
	v_sub_f32_e32 v115, v115, v0
	v_sub_f32_e32 v114, v114, v0
	v_sub_f32_e32 v113, v113, v0
	v_sub_f32_e32 v112, v112, v0
	v_sub_f32_e32 v111, v111, v0
	v_sub_f32_e32 v110, v110, v0
	v_sub_f32_e32 v109, v109, v0
	v_sub_f32_e32 v108, v108, v0
	v_sub_f32_e32 v107, v107, v0
	v_sub_f32_e32 v106, v106, v0
	v_sub_f32_e32 v105, v105, v0
	v_sub_f32_e32 v104, v104, v0
	v_sub_f32_e32 v103, v103, v0
	v_sub_f32_e32 v102, v102, v0
	v_sub_f32_e32 v101, v101, v0
	v_sub_f32_e32 v100, v100, v0
	v_sub_f32_e32 v99, v99, v0
	v_sub_f32_e32 v98, v98, v0
	v_sub_f32_e32 v97, v97, v0
	v_sub_f32_e32 v96, v96, v0
	v_mul_f32_e32 v14, v14, v15
	s_branch .LBB0_1548
.LBB0_1558:
	s_mov_b64 s[8:9], -1
	v_mov_b32_e32 v15, v14
	s_nop 1
	v_permlane32_swap_b32_e32 v14, v15
	v_max_f32_e32 v14, v14, v15
	v_max_f32_e32 v14, v14, v14
	v_max_f32_e32 v14, 0, v14
	v_exp_f32_e64 v15, -v14
	v_add_f32_e32 v219, v219, v14
	v_xor_b32_e32 v48, 0x80000000, v219
	v_mov_b32_e32 v49, v48
	v_mov_b32_e32 v50, v48
	v_mov_b32_e32 v51, v48
	v_mov_b32_e32 v52, v48
	v_mov_b32_e32 v53, v48
	v_mov_b32_e32 v54, v48
	v_mov_b32_e32 v55, v48
	v_mov_b32_e32 v56, v48
	v_mov_b32_e32 v57, v48
	v_mov_b32_e32 v58, v48
	v_mov_b32_e32 v59, v48
	v_mov_b32_e32 v60, v48
	v_mov_b32_e32 v61, v48
	v_mov_b32_e32 v62, v48
	v_mov_b32_e32 v63, v48
	s_and_saveexec_b64 s[34:35], s[6:7]
	ds_write_b32 v204, v15 offset:49152
	s_or_b64 exec, exec, s[34:35]
	v_sub_f32_e32 v95, v95, v14
	v_sub_f32_e32 v94, v94, v14
	v_sub_f32_e32 v93, v93, v14
	v_sub_f32_e32 v92, v92, v14
	v_sub_f32_e32 v91, v91, v14
	v_sub_f32_e32 v90, v90, v14
	v_sub_f32_e32 v89, v89, v14
	v_sub_f32_e32 v88, v88, v14
	v_sub_f32_e32 v87, v87, v14
	v_sub_f32_e32 v86, v86, v14
	v_sub_f32_e32 v85, v85, v14
	v_sub_f32_e32 v84, v84, v14
	v_sub_f32_e32 v83, v83, v14
	v_sub_f32_e32 v82, v82, v14
	v_sub_f32_e32 v81, v81, v14
	v_sub_f32_e32 v80, v80, v14
	v_sub_f32_e32 v79, v79, v14
	v_sub_f32_e32 v78, v78, v14
	v_sub_f32_e32 v77, v77, v14
	v_sub_f32_e32 v76, v76, v14
	v_sub_f32_e32 v75, v75, v14
	v_sub_f32_e32 v74, v74, v14
	v_sub_f32_e32 v73, v73, v14
	v_sub_f32_e32 v72, v72, v14
	v_sub_f32_e32 v71, v71, v14
	v_sub_f32_e32 v70, v70, v14
	v_sub_f32_e32 v69, v69, v14
	v_sub_f32_e32 v68, v68, v14
	v_sub_f32_e32 v67, v67, v14
	v_sub_f32_e32 v66, v66, v14
	v_sub_f32_e32 v65, v65, v14
	v_sub_f32_e32 v64, v64, v14
	v_mul_f32_e32 v223, v223, v15
	s_branch .LBB0_1551
